# P5 exchange: the timeout timestamp wait moved to the slow path
# speedup vs baseline: 1.0012x; 1.0004x over previous
;     __device__ __forceinline__ void fused(f32x4 (&acc)[2][2][4][2], const Unit& u, int wr, int wc, int fr, int fq, PG8_LAS unsigned char* lds, int wid, int lane) const {
;     ...
;         bool dead = false;
;         { const unsigned long long t0 = __builtin_amdgcn_s_memrealtime(); float q = 0.f;
;           for (;;) { bool ok = true; q = 0.f;
;             if (lane < 32) {
; #pragma unroll
;               for (int t = 0; t < 8; ++t) { const unsigned v_ = __hip_atomic_load(slotu + t, __ATOMIC_RELAXED, __HIP_MEMORY_SCOPE_AGENT); ok = ok && (v_ != 0u); q += __uint_as_float(v_); } }
;             if (__all(ok)) break;
;             if (__builtin_amdgcn_s_memrealtime() - t0 > 2000000ull) { if (lane == 0) __hip_atomic_store(tmo, 1u, __ATOMIC_RELAXED, __HIP_MEMORY_SCOPE_AGENT); dead = true; break; }
;             __builtin_amdgcn_s_sleep(2); }
.LBB0_1052:
	s_or_b64 exec, exec, s[2:3]
	s_memrealtime s[18:19]
	v_cmp_eq_u32_e64 s[2:3], 0, v194
	s_mov_b64 s[20:21], 0
	v_mov_b32_e32 v5, 0x3727c5ac
	v_mov_b32_e32 v6, 0
	v_mov_b32_e32 v7, 1
	v_mov_b64_e32 v[2:3], 0x1e8481
	s_branch .LBB0_1055
